# stack: P2 carry fold batched + u-row loads in epilogue; P1/P4 peeled first K iteration (no acc zeroing); P3/P5 zeroing overlapped with first stage loads
# speedup vs baseline: 1.0285x; 1.0023x over previous
.LBB0_364:
	v_and_b32_e32 v233, 15, v164
	v_and_b32_e32 v14, 48, v164
	v_lshlrev_b32_e32 v15, 2, v164
	s_and_b32 s43, s46, 3
	s_lshl_b32 s26, s42, 13
	v_lshl_or_b32 v14, v233, 6, v14
	v_and_b32_e32 v15, 32, v15
	s_add_i32 m0, s23, 0x18000
	v_lshl_add_u64 v[6:7], v[6:7], 0, s[34:35]
	v_bitop3_b32 v16, v14, s26, v15 bitop3:0xde
	s_lshl_b32 s26, s43, 12
	s_waitcnt vmcnt(2)
	s_barrier
	global_load_lds_dwordx4 v[6:7], off
	v_lshl_add_u64 v[4:5], v[4:5], 0, s[34:35]
	s_add_i32 m0, s23, 0x1a000
	s_add_i32 s58, s23, 0x8000
	s_add_i32 s59, s23, 0xa000
	v_bitop3_b32 v122, v14, s26, v15 bitop3:0xde
	global_load_lds_dwordx4 v[4:5], off
	v_lshl_add_u64 v[2:3], v[2:3], 0, s[34:35]
	s_mov_b32 m0, s58
	s_add_u32 s26, s0, 0x40080
	global_load_lds_dwordx4 v[2:3], off
	v_lshl_add_u64 v[0:1], v[0:1], 0, s[34:35]
	s_mov_b32 m0, s59
	s_addc_u32 s27, s1, 0
	global_load_lds_dwordx4 v[0:1], off
	s_add_i32 m0, s23, 0x1c000
	v_lshl_add_u64 v[0:1], s[26:27], 0, v[212:213]
	global_load_lds_dwordx4 v[0:1], off
	v_lshl_add_u64 v[0:1], s[26:27], 0, v[100:101]
	s_add_i32 m0, s23, 0x1e000
	s_add_u32 s60, s82, s10
	global_load_lds_dwordx4 v[0:1], off
	v_lshlrev_b32_e32 v0, 14, v12
	v_and_b32_e32 v0, 0xffff8000, v0
	s_addc_u32 s61, s83, s11
	v_lshl_add_u32 v0, v11, 11, v0
	v_and_b32_e32 v1, 1, v12
	v_lshl_or_b32 v0, v1, 6, v0
	s_add_u32 s10, s52, s10
	v_lshl_add_u32 v0, v13, 1, v0
	v_mov_b32_e32 v1, v213
	s_addc_u32 s11, s53, s11
	v_lshl_add_u64 v[110:111], s[10:11], 0, v[0:1]
	v_lshlrev_b32_e32 v0, 14, v8
	v_and_b32_e32 v0, 0xffff8000, v0
	v_lshl_add_u32 v0, v9, 11, v0
	v_and_b32_e32 v1, 1, v8
	v_lshl_or_b32 v0, v1, 6, v0
	v_lshl_add_u32 v0, v10, 1, v0
	v_mov_b32_e32 v1, v213
	v_lshl_add_u64 v[120:121], s[10:11], 0, v[0:1]
	s_add_u32 s62, s54, s8
	v_mov_b32_e32 v0, 0
	v_lshl_or_b32 v237, s42, 6, v233
	s_addc_u32 s63, s55, s9
	s_mov_b32 s64, -2
	s_mov_b64 s[8:9], 0
	v_add_u32_e32 v123, 0, v16
	v_mov_b32_e32 v1, v0
	v_mov_b32_e32 v2, v0
	v_mov_b32_e32 v3, v0
	v_mov_b32_e32 v4, v0
	v_mov_b32_e32 v5, v0
	v_mov_b32_e32 v6, v0
	v_mov_b32_e32 v7, v0
	v_mov_b32_e32 v16, v0
	v_mov_b32_e32 v17, v0
	v_mov_b32_e32 v18, v0
	v_mov_b32_e32 v19, v0
	v_mov_b32_e32 v20, v0
	v_mov_b32_e32 v21, v0
	v_mov_b32_e32 v22, v0
	v_mov_b32_e32 v23, v0
	v_mov_b32_e32 v32, v0
	v_mov_b32_e32 v33, v0
	v_mov_b32_e32 v34, v0
	v_mov_b32_e32 v35, v0
	v_mov_b32_e32 v36, v0
	v_mov_b32_e32 v37, v0
	v_mov_b32_e32 v38, v0
	v_mov_b32_e32 v39, v0
	v_mov_b32_e32 v48, v0
	v_mov_b32_e32 v49, v0
	v_mov_b32_e32 v50, v0
	v_mov_b32_e32 v51, v0
	v_mov_b32_e32 v52, v0
	v_mov_b32_e32 v53, v0
	v_mov_b32_e32 v54, v0
	v_mov_b32_e32 v55, v0
	v_mov_b32_e32 v8, v0
	v_mov_b32_e32 v9, v0
	v_mov_b32_e32 v10, v0
	v_mov_b32_e32 v11, v0
	v_mov_b32_e32 v12, v0
	v_mov_b32_e32 v13, v0
	v_mov_b32_e32 v14, v0
	v_mov_b32_e32 v15, v0
	v_mov_b32_e32 v24, v0
	v_mov_b32_e32 v25, v0
	v_mov_b32_e32 v26, v0
	v_mov_b32_e32 v27, v0
	v_mov_b32_e32 v28, v0
	v_mov_b32_e32 v29, v0
	v_mov_b32_e32 v30, v0
	v_mov_b32_e32 v31, v0
	v_mov_b32_e32 v40, v0
	v_mov_b32_e32 v41, v0
	v_mov_b32_e32 v42, v0
	v_mov_b32_e32 v43, v0
	v_mov_b32_e32 v44, v0
	v_mov_b32_e32 v45, v0
	v_mov_b32_e32 v46, v0
	v_mov_b32_e32 v47, v0
	v_mov_b32_e32 v56, v0
	v_mov_b32_e32 v57, v0
	v_mov_b32_e32 v58, v0
	v_mov_b32_e32 v59, v0
	v_mov_b32_e32 v60, v0
	v_mov_b32_e32 v61, v0
	v_mov_b32_e32 v62, v0
	v_mov_b32_e32 v63, v0
	v_mov_b32_e32 v64, v0
	v_mov_b32_e32 v65, v0
	v_mov_b32_e32 v66, v0
	v_mov_b32_e32 v67, v0
	v_mov_b32_e32 v68, v0
	v_mov_b32_e32 v69, v0
	v_mov_b32_e32 v70, v0
	v_mov_b32_e32 v71, v0
	v_mov_b32_e32 v80, v0
	v_mov_b32_e32 v81, v0
	v_mov_b32_e32 v82, v0
	v_mov_b32_e32 v83, v0
	v_mov_b32_e32 v84, v0
	v_mov_b32_e32 v85, v0
	v_mov_b32_e32 v86, v0
	v_mov_b32_e32 v87, v0
	v_mov_b32_e32 v96, v0
	v_mov_b32_e32 v97, v0
	v_mov_b32_e32 v98, v0
	v_mov_b32_e32 v99, v0
	v_mov_b32_e32 v104, v0
	v_mov_b32_e32 v105, v0
	v_mov_b32_e32 v106, v0
	v_mov_b32_e32 v107, v0
	v_mov_b32_e32 v136, v0
	v_mov_b32_e32 v137, v0
	v_mov_b32_e32 v138, v0
	v_mov_b32_e32 v139, v0
	v_mov_b32_e32 v140, v0
	v_mov_b32_e32 v141, v0
	v_mov_b32_e32 v142, v0
	v_mov_b32_e32 v143, v0
	v_mov_b32_e32 v72, v0
	v_mov_b32_e32 v73, v0
	v_mov_b32_e32 v74, v0
	v_mov_b32_e32 v75, v0
	v_mov_b32_e32 v76, v0
	v_mov_b32_e32 v77, v0
	v_mov_b32_e32 v78, v0
	v_mov_b32_e32 v79, v0
	v_mov_b32_e32 v88, v0
	v_mov_b32_e32 v89, v0
	v_mov_b32_e32 v90, v0
	v_mov_b32_e32 v91, v0
	v_mov_b32_e32 v92, v0
	v_mov_b32_e32 v93, v0
	v_mov_b32_e32 v94, v0
	v_mov_b32_e32 v95, v0
	v_mov_b32_e32 v112, v0
	v_mov_b32_e32 v113, v0
	v_mov_b32_e32 v114, v0
	v_mov_b32_e32 v115, v0
	v_mov_b32_e32 v116, v0
	v_mov_b32_e32 v117, v0
	v_mov_b32_e32 v118, v0
	v_mov_b32_e32 v119, v0
	v_mov_b32_e32 v152, v0
	v_mov_b32_e32 v153, v0
	v_mov_b32_e32 v154, v0
	v_mov_b32_e32 v155, v0
	v_mov_b32_e32 v156, v0
	v_mov_b32_e32 v157, v0
	v_mov_b32_e32 v158, v0
	v_mov_b32_e32 v159, v0
	s_waitcnt vmcnt(6)
	s_barrier

.LBB0_497:
	s_ashr_i32 s11, s10, 31
	s_lshl_b64 s[22:23], s[10:11], 19
	s_add_u32 s22, s16, s22
	s_addc_u32 s23, s17, s23
	s_and_b64 s[24:25], s[0:1], exec
	s_cselect_b32 s11, s23, s31
	s_cselect_b32 s49, s22, s30
	s_ashr_i32 s9, s8, 31
	s_lshl_b64 s[24:25], s[8:9], 19
	s_add_u32 s24, s33, s24
	s_addc_u32 s25, s34, s25
	s_and_b64 s[50:51], s[0:1], exec
	s_cselect_b32 s9, s25, s29
	s_cselect_b32 s50, s24, s28
	v_lshl_add_u32 v152, s26, 8, v164
	s_add_u32 s26, s30, 0x40080
	v_add_u32_e32 v150, 0x80, v152
	v_add_u32_e32 v148, 0x90, v152
	v_add_u32_e32 v146, 0xa0, v152
	v_add_u32_e32 v144, 0xb0, v152
	s_addc_u32 s27, s31, 0
	v_ashrrev_i32_e32 v153, 31, v152
	v_ashrrev_i32_e32 v151, 31, v150
	v_ashrrev_i32_e32 v149, 31, v148
	v_ashrrev_i32_e32 v147, 31, v146
	v_ashrrev_i32_e32 v145, 31, v144
	s_add_u32 s51, s28, 0x100
	v_lshl_add_u64 v[154:155], v[152:153], 2, s[20:21]
	v_lshl_add_u64 v[156:157], v[150:151], 2, s[20:21]
	v_lshl_add_u64 v[158:159], v[148:149], 2, s[20:21]
	v_lshl_add_u64 v[160:161], v[146:147], 2, s[20:21]
	v_lshl_add_u64 v[162:163], v[144:145], 2, s[20:21]
	s_addc_u32 s52, s29, 0
	s_mov_b32 s53, -2
	s_mov_b64 s[28:29], 0
	v_add_u32_e32 v188, s46, v165
	v_add_u32_e32 v204, s47, v165
	ds_read_b128 v[176:179], v188
	ds_read_b128 v[180:183], v188 offset:1024
	ds_read_b128 v[184:187], v188 offset:2048
	ds_read_b128 v[188:191], v188 offset:3072
	ds_read_b128 v[192:195], v204
	ds_read_b128 v[196:199], v204 offset:1024
	ds_read_b128 v[200:203], v204 offset:2048
	ds_read_b128 v[204:207], v204 offset:3072
	s_add_u32 s30, s26, 0xfffc0080
	s_addc_u32 s31, s27, -1
	s_and_b64 s[28:29], s[28:29], exec
	s_cselect_b32 s31, s11, s31
	s_cselect_b32 s30, s49, s30
	s_cselect_b32 s29, s9, s52
	s_cselect_b32 s28, s50, s51
	v_lshl_add_u64 v[242:243], s[26:27], 0, v[136:137]
	s_add_i32 m0, s36, 0xc000
	ds_read_b128 v[208:211], v167
	ds_read_b128 v[212:215], v167 offset:1024
	ds_read_b128 v[216:219], v167 offset:2048
	ds_read_b128 v[220:223], v167 offset:3072
	ds_read_b128 v[224:227], v167 offset:4096
	ds_read_b128 v[230:233], v167 offset:5120
	ds_read_b128 v[234:237], v167 offset:6144
	ds_read_b128 v[238:241], v167 offset:7168
	global_load_lds_dwordx4 v[242:243], off
	v_lshl_add_u64 v[242:243], s[26:27], 0, v[138:139]
	s_add_i32 m0, s36, 0xe000
	s_nop 0
	global_load_lds_dwordx4 v[242:243], off
	s_waitcnt vmcnt(8)
	s_waitcnt lgkmcnt(0)
	s_barrier
	s_setprio 1
	s_waitcnt lgkmcnt(0)
	v_mfma_f32_16x16x32_bf16 v[124:127], v[176:179], v[208:211], 0
	v_mfma_f32_16x16x32_bf16 v[120:123], v[184:187], v[208:211], 0
	v_mfma_f32_16x16x32_bf16 v[108:111], v[176:179], v[216:219], 0
	v_mfma_f32_16x16x32_bf16 v[104:107], v[184:187], v[216:219], 0
	v_mfma_f32_16x16x32_bf16 v[92:95], v[176:179], v[224:227], 0
	v_mfma_f32_16x16x32_bf16 v[88:91], v[184:187], v[224:227], 0
	v_mfma_f32_16x16x32_bf16 v[76:79], v[176:179], v[234:237], 0
	v_mfma_f32_16x16x32_bf16 v[72:75], v[184:187], v[234:237], 0
	v_mfma_f32_16x16x32_bf16 v[124:127], v[180:183], v[212:215], v[124:127]
	v_mfma_f32_16x16x32_bf16 v[120:123], v[188:191], v[212:215], v[120:123]
	v_mfma_f32_16x16x32_bf16 v[108:111], v[180:183], v[220:223], v[108:111]
	v_mfma_f32_16x16x32_bf16 v[104:107], v[188:191], v[220:223], v[104:107]
	v_mfma_f32_16x16x32_bf16 v[92:95], v[180:183], v[230:233], v[92:95]
	v_mfma_f32_16x16x32_bf16 v[88:91], v[188:191], v[230:233], v[88:91]
	v_mfma_f32_16x16x32_bf16 v[76:79], v[180:183], v[238:241], v[76:79]
	v_mfma_f32_16x16x32_bf16 v[72:75], v[188:191], v[238:241], v[72:75]
	s_setprio 0
	s_setprio 1
	v_mfma_f32_16x16x32_bf16 v[116:119], v[192:195], v[208:211], 0
	v_mfma_f32_16x16x32_bf16 v[112:115], v[200:203], v[208:211], 0
	v_mfma_f32_16x16x32_bf16 v[100:103], v[192:195], v[216:219], 0
	v_mfma_f32_16x16x32_bf16 v[96:99], v[200:203], v[216:219], 0
	v_mfma_f32_16x16x32_bf16 v[84:87], v[192:195], v[224:227], 0
	v_mfma_f32_16x16x32_bf16 v[80:83], v[200:203], v[224:227], 0
	v_mfma_f32_16x16x32_bf16 v[68:71], v[192:195], v[234:237], 0
	v_mfma_f32_16x16x32_bf16 v[64:67], v[200:203], v[234:237], 0
	v_mfma_f32_16x16x32_bf16 v[116:119], v[196:199], v[212:215], v[116:119]
	v_mfma_f32_16x16x32_bf16 v[112:115], v[204:207], v[212:215], v[112:115]
	v_mfma_f32_16x16x32_bf16 v[100:103], v[196:199], v[220:223], v[100:103]
	v_mfma_f32_16x16x32_bf16 v[96:99], v[204:207], v[220:223], v[96:99]
	v_mfma_f32_16x16x32_bf16 v[84:87], v[196:199], v[230:233], v[84:87]
	v_mfma_f32_16x16x32_bf16 v[80:83], v[204:207], v[230:233], v[80:83]
	v_mfma_f32_16x16x32_bf16 v[68:71], v[196:199], v[238:241], v[68:71]
	v_mfma_f32_16x16x32_bf16 v[64:67], v[204:207], v[238:241], v[64:67]
	s_setprio 0
	s_barrier
	s_add_i32 s54, s46, s35
	v_lshl_add_u64 v[242:243], s[28:29], 0, v[130:131]
	s_mov_b32 m0, s54
	ds_read_b128 v[208:211], v167 offset:16384
	ds_read_b128 v[212:215], v167 offset:17408
	ds_read_b128 v[216:219], v167 offset:18432
	ds_read_b128 v[220:223], v167 offset:19456
	ds_read_b128 v[224:227], v167 offset:20480
	ds_read_b128 v[230:233], v167 offset:21504
	ds_read_b128 v[234:237], v167 offset:22528
	ds_read_b128 v[238:241], v167 offset:23552
	global_load_lds_dwordx4 v[242:243], off
	s_add_i32 m0, s54, 0x2000
	s_add_u32 s54, s28, 0x40000
	v_lshl_add_u64 v[244:245], s[28:29], 0, v[134:135]
	s_addc_u32 s55, s29, 0
	s_add_i32 s56, s47, s35
	global_load_lds_dwordx4 v[244:245], off
	v_lshl_add_u64 v[246:247], s[54:55], 0, v[130:131]
	s_mov_b32 m0, s56
	v_lshl_add_u64 v[248:249], s[30:31], 0, v[132:133]
	global_load_lds_dwordx4 v[246:247], off
	v_lshl_add_u64 v[246:247], s[54:55], 0, v[134:135]
	s_add_i32 m0, s56, 0x2000
	s_nop 0
	global_load_lds_dwordx4 v[246:247], off
	v_lshl_add_u64 v[246:247], s[30:31], 0, v[128:129]
	s_mov_b32 m0, s36
	s_nop 0
	global_load_lds_dwordx4 v[246:247], off
	s_mov_b32 m0, s37
	s_nop 0
	global_load_lds_dwordx4 v[248:249], off
	s_waitcnt vmcnt(8)
	s_waitcnt lgkmcnt(0)
	s_barrier
	s_setprio 1
	s_waitcnt lgkmcnt(0)
	v_mfma_f32_16x16x32_bf16 v[60:63], v[176:179], v[208:211], 0
	v_mfma_f32_16x16x32_bf16 v[56:59], v[184:187], v[208:211], 0
	v_mfma_f32_16x16x32_bf16 v[44:47], v[176:179], v[216:219], 0
	v_mfma_f32_16x16x32_bf16 v[40:43], v[184:187], v[216:219], 0
	v_mfma_f32_16x16x32_bf16 v[28:31], v[176:179], v[224:227], 0
	v_mfma_f32_16x16x32_bf16 v[24:27], v[184:187], v[224:227], 0
	v_mfma_f32_16x16x32_bf16 v[12:15], v[176:179], v[234:237], 0
	v_mfma_f32_16x16x32_bf16 v[8:11], v[184:187], v[234:237], 0
	v_mfma_f32_16x16x32_bf16 v[60:63], v[180:183], v[212:215], v[60:63]
	v_mfma_f32_16x16x32_bf16 v[56:59], v[188:191], v[212:215], v[56:59]
	v_mfma_f32_16x16x32_bf16 v[44:47], v[180:183], v[220:223], v[44:47]
	v_mfma_f32_16x16x32_bf16 v[40:43], v[188:191], v[220:223], v[40:43]
	v_mfma_f32_16x16x32_bf16 v[28:31], v[180:183], v[230:233], v[28:31]
	v_mfma_f32_16x16x32_bf16 v[24:27], v[188:191], v[230:233], v[24:27]
	v_mfma_f32_16x16x32_bf16 v[12:15], v[180:183], v[238:241], v[12:15]
	v_mfma_f32_16x16x32_bf16 v[8:11], v[188:191], v[238:241], v[8:11]
	s_setprio 0
	s_setprio 1
	v_mfma_f32_16x16x32_bf16 v[52:55], v[192:195], v[208:211], 0
	v_mfma_f32_16x16x32_bf16 v[48:51], v[200:203], v[208:211], 0
	v_mfma_f32_16x16x32_bf16 v[36:39], v[192:195], v[216:219], 0
	v_mfma_f32_16x16x32_bf16 v[32:35], v[200:203], v[216:219], 0
	v_mfma_f32_16x16x32_bf16 v[20:23], v[192:195], v[224:227], 0
	v_mfma_f32_16x16x32_bf16 v[16:19], v[200:203], v[224:227], 0
	v_mfma_f32_16x16x32_bf16 v[4:7], v[192:195], v[234:237], 0
	v_mfma_f32_16x16x32_bf16 v[0:3], v[200:203], v[234:237], 0
	v_mfma_f32_16x16x32_bf16 v[52:55], v[196:199], v[212:215], v[52:55]
	v_mfma_f32_16x16x32_bf16 v[48:51], v[204:207], v[212:215], v[48:51]
	v_mfma_f32_16x16x32_bf16 v[36:39], v[196:199], v[220:223], v[36:39]
	v_mfma_f32_16x16x32_bf16 v[32:35], v[204:207], v[220:223], v[32:35]
	v_mfma_f32_16x16x32_bf16 v[20:23], v[196:199], v[230:233], v[20:23]
	v_mfma_f32_16x16x32_bf16 v[16:19], v[204:207], v[230:233], v[16:19]
	v_mfma_f32_16x16x32_bf16 v[4:7], v[196:199], v[238:241], v[4:7]
	v_mfma_f32_16x16x32_bf16 v[0:3], v[204:207], v[238:241], v[0:3]
	s_setprio 0
	s_barrier
	s_add_i32 s54, 0, 0x18000
	s_add_i32 s55, 0, 0x1c000
	v_add_u32_e32 v188, s54, v165
	v_add_u32_e32 v204, s55, v165
	ds_read_b128 v[176:179], v188
	ds_read_b128 v[180:183], v188 offset:1024
	ds_read_b128 v[184:187], v188 offset:2048
	ds_read_b128 v[188:191], v188 offset:3072
	ds_read_b128 v[192:195], v204
	ds_read_b128 v[196:199], v204 offset:1024
	ds_read_b128 v[200:203], v204 offset:2048
	ds_read_b128 v[204:207], v204 offset:3072
	s_add_u32 s30, s30, 0x40000
	s_addc_u32 s31, s31, 0
	s_mov_b32 m0, s41
	v_lshl_add_u64 v[250:251], s[30:31], 0, v[128:129]
	ds_read_b128 v[208:211], v167 offset:32768
	ds_read_b128 v[212:215], v167 offset:33792
	ds_read_b128 v[216:219], v167 offset:34816
	ds_read_b128 v[220:223], v167 offset:35840
	ds_read_b128 v[224:227], v167 offset:36864
	ds_read_b128 v[230:233], v167 offset:37888
	ds_read_b128 v[234:237], v167 offset:38912
	ds_read_b128 v[238:241], v167 offset:39936
	global_load_lds_dwordx4 v[250:251], off
	v_lshl_add_u64 v[250:251], s[30:31], 0, v[132:133]
	s_mov_b32 m0, s42
	s_nop 0
	global_load_lds_dwordx4 v[250:251], off
	s_waitcnt vmcnt(8)
	s_waitcnt lgkmcnt(0)
	s_barrier
	s_setprio 1
	s_waitcnt lgkmcnt(0)
	v_mfma_f32_16x16x32_bf16 v[124:127], v[176:179], v[208:211], v[124:127]
	v_mfma_f32_16x16x32_bf16 v[120:123], v[184:187], v[208:211], v[120:123]
	v_mfma_f32_16x16x32_bf16 v[108:111], v[176:179], v[216:219], v[108:111]
	v_mfma_f32_16x16x32_bf16 v[104:107], v[184:187], v[216:219], v[104:107]
	v_mfma_f32_16x16x32_bf16 v[92:95], v[176:179], v[224:227], v[92:95]
	v_mfma_f32_16x16x32_bf16 v[88:91], v[184:187], v[224:227], v[88:91]
	v_mfma_f32_16x16x32_bf16 v[76:79], v[176:179], v[234:237], v[76:79]
	v_mfma_f32_16x16x32_bf16 v[72:75], v[184:187], v[234:237], v[72:75]
	v_mfma_f32_16x16x32_bf16 v[124:127], v[180:183], v[212:215], v[124:127]
	v_mfma_f32_16x16x32_bf16 v[120:123], v[188:191], v[212:215], v[120:123]
	v_mfma_f32_16x16x32_bf16 v[108:111], v[180:183], v[220:223], v[108:111]
	v_mfma_f32_16x16x32_bf16 v[104:107], v[188:191], v[220:223], v[104:107]
	v_mfma_f32_16x16x32_bf16 v[92:95], v[180:183], v[230:233], v[92:95]
	v_mfma_f32_16x16x32_bf16 v[88:91], v[188:191], v[230:233], v[88:91]
	v_mfma_f32_16x16x32_bf16 v[76:79], v[180:183], v[238:241], v[76:79]
	v_mfma_f32_16x16x32_bf16 v[72:75], v[188:191], v[238:241], v[72:75]
	s_setprio 0
	s_setprio 1
	v_mfma_f32_16x16x32_bf16 v[116:119], v[192:195], v[208:211], v[116:119]
	v_mfma_f32_16x16x32_bf16 v[112:115], v[200:203], v[208:211], v[112:115]
	v_mfma_f32_16x16x32_bf16 v[100:103], v[192:195], v[216:219], v[100:103]
	v_mfma_f32_16x16x32_bf16 v[96:99], v[200:203], v[216:219], v[96:99]
	v_mfma_f32_16x16x32_bf16 v[84:87], v[192:195], v[224:227], v[84:87]
	v_mfma_f32_16x16x32_bf16 v[80:83], v[200:203], v[224:227], v[80:83]
	v_mfma_f32_16x16x32_bf16 v[68:71], v[192:195], v[234:237], v[68:71]
	v_mfma_f32_16x16x32_bf16 v[64:67], v[200:203], v[234:237], v[64:67]
	v_mfma_f32_16x16x32_bf16 v[116:119], v[196:199], v[212:215], v[116:119]
	v_mfma_f32_16x16x32_bf16 v[112:115], v[204:207], v[212:215], v[112:115]
	v_mfma_f32_16x16x32_bf16 v[100:103], v[196:199], v[220:223], v[100:103]
	v_mfma_f32_16x16x32_bf16 v[96:99], v[204:207], v[220:223], v[96:99]
	v_mfma_f32_16x16x32_bf16 v[84:87], v[196:199], v[230:233], v[84:87]
	v_mfma_f32_16x16x32_bf16 v[80:83], v[204:207], v[230:233], v[80:83]
	v_mfma_f32_16x16x32_bf16 v[68:71], v[196:199], v[238:241], v[68:71]
	v_mfma_f32_16x16x32_bf16 v[64:67], v[204:207], v[238:241], v[64:67]
	s_setprio 0
	s_barrier
	s_add_i32 s30, s54, s35
	v_lshl_add_u64 v[242:243], v[242:243], 0, s[4:5]
	s_mov_b32 m0, s30
	ds_read_b128 v[208:211], v167 offset:49152
	ds_read_b128 v[212:215], v167 offset:50176
	ds_read_b128 v[216:219], v167 offset:51200
	ds_read_b128 v[220:223], v167 offset:52224
	ds_read_b128 v[224:227], v167 offset:53248
	ds_read_b128 v[230:233], v167 offset:54272
	ds_read_b128 v[234:237], v167 offset:55296
	ds_read_b128 v[238:241], v167 offset:56320
	global_load_lds_dwordx4 v[242:243], off
	s_add_i32 m0, s30, 0x2000
	s_add_u32 s28, s28, 0x40080
	v_lshl_add_u64 v[242:243], v[244:245], 0, s[4:5]
	s_addc_u32 s29, s29, 0
	s_add_i32 s30, s55, s35
	global_load_lds_dwordx4 v[242:243], off
	v_lshl_add_u64 v[242:243], s[28:29], 0, v[130:131]
	s_mov_b32 m0, s30
	s_nop 0
	global_load_lds_dwordx4 v[242:243], off
	v_lshl_add_u64 v[242:243], s[28:29], 0, v[134:135]
	s_add_i32 m0, s30, 0x2000
	s_nop 0
	global_load_lds_dwordx4 v[242:243], off
	v_lshl_add_u64 v[242:243], v[246:247], 0, s[4:5]
	s_mov_b32 m0, s44
	s_nop 0
	global_load_lds_dwordx4 v[242:243], off
	v_lshl_add_u64 v[242:243], v[248:249], 0, s[4:5]
	s_mov_b32 m0, s45
	s_nop 0
	global_load_lds_dwordx4 v[242:243], off
	s_waitcnt vmcnt(8)
	s_waitcnt lgkmcnt(0)
	s_barrier
	s_setprio 1
	s_waitcnt lgkmcnt(0)
	v_mfma_f32_16x16x32_bf16 v[60:63], v[176:179], v[208:211], v[60:63]
	v_mfma_f32_16x16x32_bf16 v[56:59], v[184:187], v[208:211], v[56:59]
	v_mfma_f32_16x16x32_bf16 v[44:47], v[176:179], v[216:219], v[44:47]
	v_mfma_f32_16x16x32_bf16 v[40:43], v[184:187], v[216:219], v[40:43]
	v_mfma_f32_16x16x32_bf16 v[28:31], v[176:179], v[224:227], v[28:31]
	v_mfma_f32_16x16x32_bf16 v[24:27], v[184:187], v[224:227], v[24:27]
	v_mfma_f32_16x16x32_bf16 v[12:15], v[176:179], v[234:237], v[12:15]
	v_mfma_f32_16x16x32_bf16 v[8:11], v[184:187], v[234:237], v[8:11]
	v_mfma_f32_16x16x32_bf16 v[60:63], v[180:183], v[212:215], v[60:63]
	v_mfma_f32_16x16x32_bf16 v[56:59], v[188:191], v[212:215], v[56:59]
	v_mfma_f32_16x16x32_bf16 v[44:47], v[180:183], v[220:223], v[44:47]
	v_mfma_f32_16x16x32_bf16 v[40:43], v[188:191], v[220:223], v[40:43]
	v_mfma_f32_16x16x32_bf16 v[28:31], v[180:183], v[230:233], v[28:31]
	v_mfma_f32_16x16x32_bf16 v[24:27], v[188:191], v[230:233], v[24:27]
	v_mfma_f32_16x16x32_bf16 v[12:15], v[180:183], v[238:241], v[12:15]
	v_mfma_f32_16x16x32_bf16 v[8:11], v[188:191], v[238:241], v[8:11]
	s_setprio 0
	s_setprio 1
	v_mfma_f32_16x16x32_bf16 v[52:55], v[192:195], v[208:211], v[52:55]
	v_mfma_f32_16x16x32_bf16 v[48:51], v[200:203], v[208:211], v[48:51]
	v_mfma_f32_16x16x32_bf16 v[36:39], v[192:195], v[216:219], v[36:39]
	v_mfma_f32_16x16x32_bf16 v[32:35], v[200:203], v[216:219], v[32:35]
	v_mfma_f32_16x16x32_bf16 v[20:23], v[192:195], v[224:227], v[20:23]
	v_mfma_f32_16x16x32_bf16 v[16:19], v[200:203], v[224:227], v[16:19]
	v_mfma_f32_16x16x32_bf16 v[4:7], v[192:195], v[234:237], v[4:7]
	v_mfma_f32_16x16x32_bf16 v[0:3], v[200:203], v[234:237], v[0:3]
	v_mfma_f32_16x16x32_bf16 v[52:55], v[196:199], v[212:215], v[52:55]
	v_mfma_f32_16x16x32_bf16 v[48:51], v[204:207], v[212:215], v[48:51]
	v_mfma_f32_16x16x32_bf16 v[36:39], v[196:199], v[220:223], v[36:39]
	v_mfma_f32_16x16x32_bf16 v[32:35], v[204:207], v[220:223], v[32:35]
	v_mfma_f32_16x16x32_bf16 v[20:23], v[196:199], v[230:233], v[20:23]
	v_mfma_f32_16x16x32_bf16 v[16:19], v[204:207], v[230:233], v[16:19]
	v_mfma_f32_16x16x32_bf16 v[4:7], v[196:199], v[238:241], v[4:7]
	v_mfma_f32_16x16x32_bf16 v[0:3], v[204:207], v[238:241], v[0:3]
	s_setprio 0
	s_barrier
	s_add_i32 s53, s53, 2
	s_add_u32 s26, s26, 0x100
	s_addc_u32 s27, s27, 0
	s_add_u32 s51, s51, 0x100
	s_addc_u32 s52, s52, 0
	s_branch .LBB0_499

.LBB0_598:
	v_and_b32_e32 v183, 15, v182
	v_and_b32_e32 v14, 48, v182
	v_lshlrev_b32_e32 v15, 2, v182
	s_and_b32 s3, s37, 3
	s_lshl_b32 s22, s41, 13
	v_lshl_or_b32 v14, v183, 6, v14
	v_and_b32_e32 v15, 32, v15
	s_add_i32 m0, s43, 0x18000
	v_lshl_add_u64 v[6:7], v[6:7], 0, s[4:5]
	s_lshl_b32 s47, s41, 6
	v_bitop3_b32 v16, v14, s22, v15 bitop3:0xde
	s_lshl_b32 s22, s3, 12
	s_waitcnt vmcnt(2)
	s_barrier
	global_load_lds_dwordx4 v[6:7], off
	v_lshl_add_u64 v[4:5], v[4:5], 0, s[4:5]
	s_add_i32 m0, s43, 0x1a000
	s_add_i32 s48, s43, 0x8000
	s_add_i32 s49, s43, 0xa000
	v_bitop3_b32 v138, v14, s22, v15 bitop3:0xde
	global_load_lds_dwordx4 v[4:5], off
	v_lshl_add_u64 v[2:3], v[2:3], 0, s[4:5]
	s_mov_b32 m0, s48
	s_add_u32 s22, s0, 0x100080
	global_load_lds_dwordx4 v[2:3], off
	v_lshl_add_u64 v[0:1], v[0:1], 0, s[4:5]
	s_mov_b32 m0, s49
	s_addc_u32 s23, s1, 0
	global_load_lds_dwordx4 v[0:1], off
	s_add_i32 m0, s43, 0x1c000
	v_lshl_add_u64 v[0:1], s[22:23], 0, v[212:213]
	global_load_lds_dwordx4 v[0:1], off
	v_lshl_add_u64 v[0:1], s[22:23], 0, v[128:129]
	s_add_i32 m0, s43, 0x1e000
	s_add_u32 s50, s82, s20
	global_load_lds_dwordx4 v[0:1], off
	v_lshlrev_b32_e32 v0, 16, v12
	v_and_b32_e32 v0, 0xfffe0000, v0
	s_addc_u32 s51, s83, s21
	v_lshl_add_u32 v0, v11, 13, v0
	v_and_b32_e32 v1, 1, v12
	v_lshl_or_b32 v0, v1, 6, v0
	s_add_u32 s20, s29, s20
	v_lshl_add_u32 v0, v13, 1, v0
	v_mov_b32_e32 v1, v213
	s_addc_u32 s21, s30, s21
	v_lshl_add_u64 v[134:135], s[20:21], 0, v[0:1]
	v_lshlrev_b32_e32 v0, 16, v8
	v_and_b32_e32 v0, 0xfffe0000, v0
	v_lshl_add_u32 v0, v9, 13, v0
	v_and_b32_e32 v1, 1, v8
	v_lshl_or_b32 v0, v1, 6, v0
	v_lshl_add_u32 v0, v10, 1, v0
	v_mov_b32_e32 v1, v213
	v_lshl_add_u64 v[136:137], s[20:21], 0, v[0:1]
	s_add_u32 s52, s31, s18
	v_mov_b32_e32 v0, 0
	v_or_b32_e32 v216, s47, v183
	s_addc_u32 s53, s33, s19
	s_mov_b32 s54, -2
	s_mov_b64 s[18:19], 0
	v_add_u32_e32 v139, 0, v16
	v_mov_b32_e32 v1, v0
	v_mov_b32_e32 v2, v0
	v_mov_b32_e32 v3, v0
	v_mov_b32_e32 v4, v0
	v_mov_b32_e32 v5, v0
	v_mov_b32_e32 v6, v0
	v_mov_b32_e32 v7, v0
	v_mov_b32_e32 v12, v0
	v_mov_b32_e32 v13, v0
	v_mov_b32_e32 v14, v0
	v_mov_b32_e32 v15, v0
	v_mov_b32_e32 v20, v0
	v_mov_b32_e32 v21, v0
	v_mov_b32_e32 v22, v0
	v_mov_b32_e32 v23, v0
	v_mov_b32_e32 v32, v0
	v_mov_b32_e32 v33, v0
	v_mov_b32_e32 v34, v0
	v_mov_b32_e32 v35, v0
	v_mov_b32_e32 v36, v0
	v_mov_b32_e32 v37, v0
	v_mov_b32_e32 v38, v0
	v_mov_b32_e32 v39, v0
	v_mov_b32_e32 v44, v0
	v_mov_b32_e32 v45, v0
	v_mov_b32_e32 v46, v0
	v_mov_b32_e32 v47, v0
	v_mov_b32_e32 v52, v0
	v_mov_b32_e32 v53, v0
	v_mov_b32_e32 v54, v0
	v_mov_b32_e32 v55, v0
	v_mov_b32_e32 v8, v0
	v_mov_b32_e32 v9, v0
	v_mov_b32_e32 v10, v0
	v_mov_b32_e32 v11, v0
	v_mov_b32_e32 v16, v0
	v_mov_b32_e32 v17, v0
	v_mov_b32_e32 v18, v0
	v_mov_b32_e32 v19, v0
	v_mov_b32_e32 v24, v0
	v_mov_b32_e32 v25, v0
	v_mov_b32_e32 v26, v0
	v_mov_b32_e32 v27, v0
	v_mov_b32_e32 v28, v0
	v_mov_b32_e32 v29, v0
	v_mov_b32_e32 v30, v0
	v_mov_b32_e32 v31, v0
	v_mov_b32_e32 v40, v0
	v_mov_b32_e32 v41, v0
	v_mov_b32_e32 v42, v0
	v_mov_b32_e32 v43, v0
	v_mov_b32_e32 v48, v0
	v_mov_b32_e32 v49, v0
	v_mov_b32_e32 v50, v0
	v_mov_b32_e32 v51, v0
	v_mov_b32_e32 v56, v0
	v_mov_b32_e32 v57, v0
	v_mov_b32_e32 v58, v0
	v_mov_b32_e32 v59, v0
	v_mov_b32_e32 v60, v0
	v_mov_b32_e32 v61, v0
	v_mov_b32_e32 v62, v0
	v_mov_b32_e32 v63, v0
	v_mov_b32_e32 v64, v0
	v_mov_b32_e32 v65, v0
	v_mov_b32_e32 v66, v0
	v_mov_b32_e32 v67, v0
	v_mov_b32_e32 v68, v0
	v_mov_b32_e32 v69, v0
	v_mov_b32_e32 v70, v0
	v_mov_b32_e32 v71, v0
	v_mov_b32_e32 v76, v0
	v_mov_b32_e32 v77, v0
	v_mov_b32_e32 v78, v0
	v_mov_b32_e32 v79, v0
	v_mov_b32_e32 v84, v0
	v_mov_b32_e32 v85, v0
	v_mov_b32_e32 v86, v0
	v_mov_b32_e32 v87, v0
	v_mov_b32_e32 v96, v0
	v_mov_b32_e32 v97, v0
	v_mov_b32_e32 v98, v0
	v_mov_b32_e32 v99, v0
	v_mov_b32_e32 v100, v0
	v_mov_b32_e32 v101, v0
	v_mov_b32_e32 v102, v0
	v_mov_b32_e32 v103, v0
	v_mov_b32_e32 v104, v0
	v_mov_b32_e32 v105, v0
	v_mov_b32_e32 v106, v0
	v_mov_b32_e32 v107, v0
	v_mov_b32_e32 v108, v0
	v_mov_b32_e32 v109, v0
	v_mov_b32_e32 v110, v0
	v_mov_b32_e32 v111, v0
	v_mov_b32_e32 v72, v0
	v_mov_b32_e32 v73, v0
	v_mov_b32_e32 v74, v0
	v_mov_b32_e32 v75, v0
	v_mov_b32_e32 v80, v0
	v_mov_b32_e32 v81, v0
	v_mov_b32_e32 v82, v0
	v_mov_b32_e32 v83, v0
	v_mov_b32_e32 v88, v0
	v_mov_b32_e32 v89, v0
	v_mov_b32_e32 v90, v0
	v_mov_b32_e32 v91, v0
	v_mov_b32_e32 v92, v0
	v_mov_b32_e32 v93, v0
	v_mov_b32_e32 v94, v0
	v_mov_b32_e32 v95, v0
	v_mov_b32_e32 v112, v0
	v_mov_b32_e32 v113, v0
	v_mov_b32_e32 v114, v0
	v_mov_b32_e32 v115, v0
	v_mov_b32_e32 v116, v0
	v_mov_b32_e32 v117, v0
	v_mov_b32_e32 v118, v0
	v_mov_b32_e32 v119, v0
	v_mov_b32_e32 v120, v0
	v_mov_b32_e32 v121, v0
	v_mov_b32_e32 v122, v0
	v_mov_b32_e32 v123, v0
	v_mov_b32_e32 v124, v0
	v_mov_b32_e32 v125, v0
	v_mov_b32_e32 v126, v0
	v_mov_b32_e32 v127, v0
	s_waitcnt vmcnt(6)
	s_barrier
